# FoX key-tile loop: early-exit flag wait/test moved from right behind the loop barrier to the tile's first LDS wait (rotation of the loop edge work)
# baseline (speedup 1.0000x reference)
; #define LAS __attribute__((address_space(3)))
; __device__ __forceinline__ float bflo(unsigned u) { return __uint_as_float(u << 16); }
; template <int MODE>
; __device__ __forceinline__ void attn_item(const AttnP& p, int b, int h, int qb, LAS unsigned char* lds) {
;     ...
;         float sc = 0.125f * LOG2E;
;         if (MODE != 1) { ss += __shfl_xor(ss, 32); sc *= 1.0f / sqrtf(ss * (1.0f / 64.0f) + 1e-6f); }
; #pragma unroll
;         for (int ks = 0; ks < 4; ++ks) {
;             u32x4 o;
; #pragma unroll
;             for (int e = 0; e < 4; ++e) {
;                 float lo = bflo(raw[ks][e]) * sc, hi = bfhi(raw[ks][e]) * sc;
;                 if (MODE != 1) {
;                     const int d = ks * 16 + hh * 8 + 2 * e;
;                     const float* gq = p.qk_gain + ((MODE == 0) ? 0 : 128); const float* gk = gq + 64;
;                     lo *= gq[d] * gk[d]; hi *= gq[d + 1] * gk[d + 1];
;                 }
;                 o[e] = pk2(lo, hi);
;             }
;             Qf[c][ks] = __builtin_bit_cast(bf16x8, o);
;             if (QPARK) *(LAS u32x4*)(lds + QP_OFF + w * 8192 + ((c * 4 + ks) * 64 + lane) * 16) = o;
;         }
;     }
;     if (MODE == 0) { LAS float* tab = (LAS float*)(lds + TAB_OFF); if (tid < 256) tab[tid] = p.biasT[h * 256 + tid]; }
;     LAS unsigned* flags = (LAS unsigned*)(lds + FLAG_OFF);
;     if (MODE == 1 && tid < 16) flags[tid] = 0u;
;     f32x16 O[NC][DV / 32];
; #pragma unroll
;     for (int c = 0; c < NC; ++c)
; #pragma unroll
;         for (int d = 0; d < DV / 32; ++d)
; #pragma unroll
;             for (int i = 0; i < 16; ++i) O[c][d][i] = 0.f;
;     float mrun[NC], lsum[NC];
; #pragma unroll
;     for (int c = 0; c < NC; ++c) { mrun[c] = -1e30f; lsum[c] = 0.f; }
;     float R2 = 0.f; bool mydone = false;
;     float carry = 0.f, bq0 = 0.f, qk2 = 0.f;
;     LAS unsigned* cflags = flags + 32;
;     if (MODE == 2) {
;         if (tid < 4) cflags[tid] = 0u;
;         float gq_ = fabsf(p.qk_gain[128 + lane]), gk_ = fabsf(p.qk_gain[192 + lane]);
; #pragma unroll
;         for (int o_ = 1; o_ < 64; o_ <<= 1) { gq_ = fmaxf(gq_, __shfl_xor(gq_, o_)); gk_ = fmaxf(gk_, __shfl_xor(gk_, o_)); }
;         qk2 = 8.0f * gq_ * gk_ * LOG2E * 1.02f;
;     ...
;     ATT_LOAD(jt_max);
;     ATT_STORE(0, jt_max);
;     __syncthreads();
;     float mfix = 0.f;
;     if (MODE == 2) mfix = qk2;
.LBB0_225:
	v_pk_mul_f32 v[12:13], v[12:13], v[16:17]
	v_add_f32_e32 v16, v125, v126
	v_fmamk_f32 v16, v16, 0x3c800000, v211
	v_mul_f32_e32 v17, 0x4f800000, v16
	v_cmp_gt_f32_e32 vcc, s55, v16
	v_pk_mul_f32 v[2:3], v[2:3], v[6:7]
	v_pk_mul_f32 v[6:7], v[28:29], v[36:37]
	v_pk_mul_f32 v[28:29], v[40:41], v[48:49]
	v_cndmask_b32_e32 v40, v16, v17, vcc
	v_sqrt_f32_e32 v41, v40
	v_pk_mul_f32 v[30:31], v[30:31], v[42:43]
	v_pk_mul_f32 v[18:19], v[18:19], v[22:23]
	v_pk_mul_f32 v[20:21], v[20:21], v[24:25]
	v_add_u32_e32 v42, -1, v41
	v_fma_f32 v43, -v42, v41, v40
	v_cmp_ge_f32_e64 s[0:1], 0, v43
	v_add_u32_e32 v43, 1, v41
	v_pk_mul_f32 v[26:27], v[26:27], v[34:35]
	v_cndmask_b32_e64 v42, v41, v42, s[0:1]
	v_fma_f32 v41, -v43, v41, v40
	v_cmp_lt_f32_e64 s[0:1], 0, v41
	v_pk_mul_f32 v[34:35], v[38:39], v[46:47]
	v_pk_mul_f32 v[38:39], v[58:59], v[72:73]
	v_cndmask_b32_e64 v41, v42, v43, s[0:1]
	v_mul_f32_e32 v42, 0x37800000, v41
	v_cndmask_b32_e32 v41, v41, v42, vcc
	v_cmp_class_f32_e32 vcc, v40, v212
	v_pk_mul_f32 v[16:17], v[50:51], v[54:55]
	v_pk_mul_f32 v[36:37], v[60:61], v[74:75]
	v_cndmask_b32_e32 v40, v41, v40, vcc
	v_div_scale_f32 v41, s[0:1], v40, v40, 1.0
	v_rcp_f32_e32 v42, v41
	v_pk_mul_f32 v[10:11], v[10:11], v[14:15]
	v_pk_mul_f32 v[14:15], v[52:53], v[56:57]
	v_max_f32_e32 v93, v93, v93
	v_fma_f32 v22, -v41, v42, 1.0
	v_fmac_f32_e32 v42, v22, v42
	v_div_scale_f32 v22, vcc, 1.0, v40, 1.0
	v_mul_f32_e32 v23, v22, v42
	v_fma_f32 v24, -v41, v23, v22
	v_fmac_f32_e32 v23, v24, v42
	v_fma_f32 v22, -v41, v23, v22
	v_div_fmas_f32 v22, v22, v42, v23
	v_div_fixup_f32 v22, v22, v40, 1.0
	v_mul_f32_e32 v22, 0x3e38aa3b, v22
	v_pk_mul_f32 v[24:25], v[22:23], v[106:107] op_sel_hi:[0,1]
	v_pk_mul_f32 v[18:19], v[18:19], v[24:25]
	v_max_f32_e32 v91, v91, v91
	v_cvt_pk_bf16_f32 v72, v18, v19
	v_pk_mul_f32 v[18:19], v[22:23], v[104:105] op_sel_hi:[0,1]
	v_pk_mul_f32 v[18:19], v[20:21], v[18:19]
	v_pk_mul_f32 v[32:33], v[32:33], v[44:45]
	v_cvt_pk_bf16_f32 v73, v18, v19
	v_pk_mul_f32 v[18:19], v[22:23], v[102:103] op_sel_hi:[0,1]
	v_pk_mul_f32 v[16:17], v[16:17], v[18:19]
	v_max_f32_e32 v91, v91, v93
	v_cvt_pk_bf16_f32 v74, v16, v17
	v_pk_mul_f32 v[16:17], v[22:23], v[100:101] op_sel_hi:[0,1]
	v_pk_mul_f32 v[14:15], v[14:15], v[16:17]
	v_mov_b32_e32 v93, v83
	v_cvt_pk_bf16_f32 v75, v14, v15
	v_pk_mul_f32 v[14:15], v[22:23], v[76:77] op_sel_hi:[0,1]
	v_pk_mul_f32 v[10:11], v[10:11], v[14:15]
	v_mov_b32_e32 v83, v109
	v_cvt_pk_bf16_f32 v76, v10, v11
	v_pk_mul_f32 v[10:11], v[22:23], v[98:99] op_sel_hi:[0,1]
	v_pk_mul_f32 v[10:11], v[10:11], v[12:13]
	v_max_f32_e32 v121, v121, v121
	v_cvt_pk_bf16_f32 v77, v10, v11
	v_pk_mul_f32 v[10:11], v[22:23], v[78:79] op_sel_hi:[0,1]
	v_pk_mul_f32 v[10:11], v[10:11], v[38:39]
	v_max_f32_e32 v63, v63, v63
	v_cvt_pk_bf16_f32 v78, v10, v11
	v_pk_mul_f32 v[10:11], v[22:23], v[96:97] op_sel_hi:[0,1]
	v_pk_mul_f32 v[10:11], v[10:11], v[36:37]
	v_max_f32_e32 v63, v63, v121
	v_cvt_pk_bf16_f32 v79, v10, v11
	v_pk_mul_f32 v[10:11], v[22:23], v[80:81] op_sel_hi:[0,1]
	v_pk_mul_f32 v[10:11], v[10:11], v[30:31]
	v_mul_f32_e32 v63, 0x41000000, v63
	v_cvt_pk_bf16_f32 v80, v10, v11
	v_pk_mul_f32 v[10:11], v[22:23], v[94:95] op_sel_hi:[0,1]
	v_pk_mul_f32 v[10:11], v[10:11], v[32:33]
	v_mul_f32_e32 v63, v91, v63
	v_cvt_pk_bf16_f32 v81, v10, v11
	v_pk_mul_f32 v[10:11], v[22:23], v[82:83] op_sel_hi:[0,1]
	v_pk_mul_f32 v[10:11], v[10:11], v[34:35]
	v_mov_b32_e32 v91, v85
	v_cvt_pk_bf16_f32 v82, v10, v11
	v_pk_mul_f32 v[10:11], v[22:23], v[92:93] op_sel_hi:[0,1]
	v_mov_b32_e32 v85, v111
	v_pk_mul_f32 v[10:11], v[10:11], v[28:29]
	v_mul_f32_e32 v63, 0x3fb8aa3b, v63
	v_cvt_pk_bf16_f32 v83, v10, v11
	v_pk_mul_f32 v[10:11], v[22:23], v[84:85] op_sel_hi:[0,1]
	v_pk_mul_f32 v[10:11], v[10:11], v[26:27]
	v_mul_f32_e32 v121, 0x3f828f5c, v63
	v_cvt_pk_bf16_f32 v84, v10, v11
	v_pk_mul_f32 v[10:11], v[22:23], v[90:91] op_sel_hi:[0,1]
	v_mov_b32_e32 v63, v87
	v_mov_b32_e32 v87, v113
	v_pk_mul_f32 v[6:7], v[10:11], v[6:7]
	v_pk_mul_f32 v[4:5], v[4:5], v[8:9]
	v_cvt_pk_bf16_f32 v85, v6, v7
	v_pk_mul_f32 v[6:7], v[22:23], v[86:87] op_sel_hi:[0,1]
	v_pk_mul_f32 v[2:3], v[6:7], v[2:3]
	v_lshlrev_b32_e32 v94, 2, v124
	v_cvt_pk_bf16_f32 v86, v2, v3
	v_pk_mul_f32 v[2:3], v[22:23], v[62:63] op_sel_hi:[0,1]
	v_pk_mul_f32 v[2:3], v[2:3], v[4:5]
	v_cmp_ne_u32_e32 vcc, 63, v130
	v_cvt_pk_bf16_f32 v87, v2, v3
	v_lshl_add_u64 v[2:3], s[68:69], 0, v[0:1]
	v_lshrrev_b32_e32 v0, 2, v123
	v_lshl_add_u64 v[90:91], v[2:3], 0, s[92:93]
	v_and_or_b32 v0, v0, 3, v94
	v_lshlrev_b32_e32 v3, 2, v123
	v_and_b32_e32 v2, 16, v123
	v_and_b32_e32 v3, 12, v3
	v_mul_u32_u24_e32 v0, 0x60, v0
	v_or3_b32 v0, v3, v2, v0
	v_lshlrev_b32_e32 v97, 1, v0
	v_addc_co_u32_e32 v0, vcc, 0, v216, vcc
	v_cmp_gt_u32_e32 vcc, 62, v130
	v_lshlrev_b32_e32 v101, 2, v0
	s_or_b32 s31, s27, 31
	v_cndmask_b32_e64 v0, 0, 2, vcc
	v_cmp_gt_u32_e32 vcc, 60, v130
	v_add_lshl_u32 v102, v0, v216, 2
	s_add_u32 s18, s84, s18
	v_cndmask_b32_e64 v0, 0, 4, vcc
	v_cmp_gt_u32_e32 vcc, 56, v130
	v_add_lshl_u32 v103, v0, v216, 2
	s_addc_u32 s19, s85, 0
	v_cndmask_b32_e64 v0, 0, 8, vcc
	v_cmp_gt_u32_e32 vcc, 48, v130
	v_add_lshl_u32 v104, v0, v216, 2
	s_add_i32 s15, s26, 0xf80
	v_cndmask_b32_e64 v0, 0, 16, vcc
	v_add_lshl_u32 v105, v0, v216, 2
	s_lshl_b32 s14, s22, 8
	v_add_u32_e32 v0, s15, v89
	s_sub_i32 s33, 0xfff, s14
	v_subrev_u32_e32 v0, s14, v0
	s_movk_i32 s14, 0x140
	v_mov_b32_e32 v14, v1
	v_mov_b32_e32 v15, v1
	v_mul_lo_u32 v92, v0, s14
	v_mov_b32_e32 v0, v1
	v_mov_b32_e32 v2, v1
	v_mov_b32_e32 v3, v1
	v_mov_b32_e32 v4, v1
	v_mov_b32_e32 v5, v1
	v_mov_b32_e32 v6, v1
	v_mov_b32_e32 v7, v1
	v_mov_b32_e32 v8, v1
	v_mov_b32_e32 v9, v1
	v_mov_b32_e32 v10, v1
	v_mov_b32_e32 v11, v1
	v_mov_b32_e32 v12, v1
	v_mov_b32_e32 v13, v1
	v_mov_b64_e32 v[30:31], v[14:15]
	v_mov_b64_e32 v[46:47], v[14:15]
	s_mov_b32 s30, 0
	v_cmp_eq_u32_e64 s[0:1], 0, v89
	v_fmaak_f32 v95, 2.0, v121, 0x41400000
	v_mul_u32_u24_e32 v96, 0x90, v122
	v_or_b32_e32 v98, 0x1800, v97
	v_add_u32_e32 v99, 0x2400, v97
	v_add_u32_e32 v100, 0xc00, v97
	v_cmp_eq_u32_e64 s[16:17], 63, v89
	v_cmp_gt_u32_e64 s[4:5], 62, v89
	v_cmp_gt_u32_e64 s[6:7], 60, v89
	v_cmp_gt_u32_e64 s[8:9], 56, v89
	v_cmp_gt_u32_e64 s[10:11], 48, v89
	v_cmp_gt_u32_e64 s[12:13], 32, v89
	v_add_u32_e32 v106, s26, v127
	s_mov_b32 s34, s29
	v_mov_b64_e32 v[28:29], v[12:13]
	v_mov_b64_e32 v[26:27], v[10:11]
	v_mov_b64_e32 v[24:25], v[8:9]
	v_mov_b64_e32 v[22:23], v[6:7]
	v_mov_b64_e32 v[20:21], v[4:5]
	v_mov_b64_e32 v[18:19], v[2:3]
	v_mov_b64_e32 v[16:17], v[0:1]
	v_mov_b64_e32 v[44:45], v[12:13]
	v_mov_b64_e32 v[42:43], v[10:11]
	v_mov_b64_e32 v[40:41], v[8:9]
	v_mov_b64_e32 v[38:39], v[6:7]
	v_mov_b64_e32 v[36:37], v[4:5]
	v_mov_b64_e32 v[34:35], v[2:3]
	v_mov_b64_e32 v[32:33], v[0:1]
	v_mov_b32_e32 v0, 0
	s_waitcnt lgkmcnt(0)
	s_barrier
	v_mov_b32_e32 v121, 0
	v_mov_b32_e32 v248, 0
	s_branch .LBB0_228

; template <int MODE>
; __device__ __forceinline__ void attn_item(const AttnP& p, int b, int h, int qb, LAS unsigned char* lds) {
;     ...
;         if (has_next) { ATT_STORE(buf ^ 1, jt - 1); }
;         __syncthreads();
;         if (MODE == 2) { if (cflags[jt & 3]) break; }
.LBB0_227:
	s_and_b32 s14, s34, 3
	s_lshl_b32 s14, s14, 2
	s_add_i32 s14, s14, 0
	v_mov_b32_e32 v248, s14
	s_waitcnt lgkmcnt(0)
	s_barrier
	ds_read_b32 v248, v248 offset:44672
	s_add_i32 s30, s30, 1
	s_sub_i32 s33, s33, 64
	v_add_u32_e32 v92, 0xffffb000, v92
	s_add_i32 s34, s34, -1
	s_cmp_eq_u32 s34, -1
	s_cbranch_scc1 .Lfox_exit_late

; template <int MODE>
; __device__ __forceinline__ void attn_item(const AttnP& p, int b, int h, int qb, LAS unsigned char* lds) {
;     ...
;             const int kp0 = k0 + 32 * kb2;
;             bool active = (MODE == 1) ? (kp0 <= qw + 30) : (kp0 <= qw + 31);
;             if (MODE == 1) active = active && !mydone;
;             if (active) {
;                 f32x16 S[NC];
;     ...
;                 if (MODE == 1) ATT_QK(0, 0.f);
;                 const bool need_mask = (MODE == 1) ? (kp0 + 31 >= qw) : (kp0 + 31 > qw);
.LBB0_232:
	s_and_b32 s35, s30, 1
	s_mul_i32 s24, s35, 0x5500
	s_add_i32 s36, s24, 0
	v_add_u32_e32 v2, s36, v88
	s_sub_i32 s24, s33, 31
	v_lshl_add_u32 v8, v94, 2, s36
	s_cmp_le_i32 s33, s27
	s_cbranch_scc1 .Lfox_far
	s_waitcnt lgkmcnt(0)
	v_cmp_ne_u32_e32 vcc, 0, v248
	s_nop 3
	s_cbranch_vccnz .LBB0_242
	s_cmp_gt_i32 s24, s31
	v_add_u32_e32 v6, v2, v96
	v_add_u32_e32 v7, s33, v94
	s_cbranch_scc0 .LBB0_235
	s_sub_i32 s24, s33, 63
	s_cmp_gt_i32 s24, s31
	s_cbranch_scc0 .LBB0_236

; #define LAS __attribute__((address_space(3)))
; template <int MODE>
; __device__ __forceinline__ void attn_item(const AttnP& p, int b, int h, int qb, LAS unsigned char* lds) {
;     ...
;                     if (MODE == 0) {
;                         const LAS float* tab = (const LAS float*)(lds + TAB_OFF);
;                         if (qw - (kp0 + 31) >= 128) {
;                             const float cb = tab[255] - mfix;
; #pragma unroll
;                             for (int c = 0; c < NC; ++c) { ATT_QK(c, cb); ATT_TAIL(c); }
;                         } else {
;                             float binit[16];
; #pragma unroll
;                             for (int i = 0; i < 16; ++i) {
;                                 const int dist = qrow - (kp0 + crow(i, hh));
;                                 binit[i] = (dist < 0) ? -3e38f : (tab[dist > 255 ? 255 : dist] - mfix);
;                             }
; #pragma unroll
;                             for (int c = 0; c < NC; ++c) { ATT_QK(c, binit[i]); ATT_TAIL(c); }
;                         }
;                     } else {
;                         float binit[16];
;                         const LAS float* bl = (const LAS float*)(vtb + VT_BYTES) + 32 * kb2 + 4 * hh;
; #pragma unroll
;                         for (int g = 0; g < 4; ++g) {
;                             const f32x4 t = *(const LAS f32x4*)(bl + 8 * g);
; #pragma unroll
;                             for (int e = 0; e < 4; ++e) binit[4 * g + e] = (need_mask && (kp0 + crow(4 * g + e, hh) > qrow)) ? -3e38f : (t[e] - mfix);
;                         }
;                         ATT_QK(0, binit[i]); ATT_TAIL(0);
;                     }
;     ...
;                 }
; #pragma unroll
;                 for (int t2 = 0; t2 < 2; ++t2)
; #pragma unroll
;                     for (int d = 0; d < DV / 32; ++d) {
;                         const LAS unsigned char* vp = vtb + ((32 * kb2 + 16 * t2 + 4 * hh + ((lane & 15) >> 2)) * VPT + d * 32 + 16 * ((lane >> 4) & 1) + 4 * (lane & 3)) * 2;
;                         const s16x4 lo = vtr(vp), hi = vtr(vp + 8 * VPT * 2);
;                         const bf16x8 va = __builtin_shufflevector(lo, hi, 0, 1, 2, 3, 4, 5, 6, 7);
; #pragma unroll
;                         for (int c = 0; c < NC; ++c) O[c][d] = MFMA32(va, pb[c][t2], O[c][d]);
;                     }
.Lfox_exit_late:
	s_waitcnt lgkmcnt(0)
	s_branch .LBB0_242
.Lfox_far:
	v_add_u32_e32 v6, v2, v96
	v_add_u32_e32 v193, s36, v98
	v_add_u32_e32 v221, s36, v99
	v_add_u32_e32 v246, s36, v97
	v_add_u32_e32 v247, s36, v100
	ds_read_b128 v[140:143], v8 offset:21632
	ds_read_b128 v[144:147], v8 offset:21664
	ds_read_b128 v[148:151], v8 offset:21696
	ds_read_b128 v[152:155], v8 offset:21728
	ds_read_b128 v[172:175], v6 offset:4608
	ds_read_b128 v[176:179], v6 offset:4640
	ds_read_b128 v[180:183], v6 offset:4672
	ds_read_b128 v[184:187], v6 offset:4704
	ds_read_b128 v[156:159], v8 offset:21504
	ds_read_b128 v[160:163], v8 offset:21536
	ds_read_b128 v[164:167], v8 offset:21568
	ds_read_b128 v[168:171], v8 offset:21600
	s_waitcnt lgkmcnt(7)
	v_cmp_ne_u32_e32 vcc, 0, v248
	s_nop 3
	s_cbranch_vccnz .Lfox_exit_late
	v_mfma_f32_32x32x16_bf16 v[140:155], v[172:175], v[72:75], v[140:155]
	ds_read_b128 v[222:225], v6 offset:0
	s_waitcnt lgkmcnt(7)
	v_mfma_f32_32x32x16_bf16 v[140:155], v[176:179], v[76:79], v[140:155]
	ds_read_b128 v[226:229], v6 offset:32
	s_waitcnt lgkmcnt(7)
	v_mfma_f32_32x32x16_bf16 v[140:155], v[180:183], v[80:83], v[140:155]
	ds_read_b128 v[230:233], v6 offset:64
	s_waitcnt lgkmcnt(7)
	v_mfma_f32_32x32x16_bf16 v[140:155], v[184:187], v[84:87], v[140:155]
	ds_read_b128 v[234:237], v6 offset:96
	ds_read_b64_tr_b16 v[188:189], v193 offset:9216
	ds_read_b64_tr_b16 v[190:191], v193 offset:10752
	ds_read_b64_tr_b16 v[206:207], v193 offset:9280
	ds_read_b64_tr_b16 v[208:209], v193 offset:10816
	s_waitcnt lgkmcnt(7)
	v_mfma_f32_32x32x16_bf16 v[156:171], v[222:225], v[72:75], v[156:171]
	ds_read_b64_tr_b16 v[238:239], v221 offset:9216
	ds_read_b64_tr_b16 v[240:241], v221 offset:10752
	ds_read_b64_tr_b16 v[242:243], v221 offset:9280
	ds_read_b64_tr_b16 v[244:245], v221 offset:10816
	s_nop 1
	v_exp_f32_e32 v140, v140
	v_exp_f32_e32 v141, v141
	v_exp_f32_e32 v142, v142
	v_add_f32_e32 v192, v140, v141
	v_exp_f32_e32 v143, v143
	v_add_f32_e32 v192, v142, v192
	v_exp_f32_e32 v144, v144
	v_add_f32_e32 v192, v143, v192
	v_exp_f32_e32 v145, v145
	v_add_f32_e32 v192, v144, v192
	s_waitcnt lgkmcnt(10)
	v_mfma_f32_32x32x16_bf16 v[156:171], v[226:229], v[76:79], v[156:171]
	ds_read_b64_tr_b16 v[180:181], v246 offset:9216
	ds_read_b64_tr_b16 v[182:183], v246 offset:10752
	ds_read_b64_tr_b16 v[184:185], v246 offset:9280
	ds_read_b64_tr_b16 v[186:187], v246 offset:10816
	v_exp_f32_e32 v146, v146
	v_add_f32_e32 v192, v145, v192
	v_exp_f32_e32 v147, v147
	v_add_f32_e32 v192, v146, v192
	v_cvt_pk_bf16_f32 v140, v140, v141
	v_add_f32_e32 v192, v147, v192
	v_cvt_pk_bf16_f32 v141, v142, v143
	v_cvt_pk_bf16_f32 v142, v144, v145
	v_cvt_pk_bf16_f32 v143, v146, v147
	v_exp_f32_e32 v148, v148
	s_waitcnt lgkmcnt(13)
	v_mfma_f32_32x32x16_bf16 v[156:171], v[230:233], v[80:83], v[156:171]
	v_exp_f32_e32 v149, v149
	v_add_f32_e32 v192, v148, v192
	v_exp_f32_e32 v150, v150
	v_add_f32_e32 v192, v149, v192
	v_exp_f32_e32 v151, v151
	v_add_f32_e32 v192, v150, v192
	v_exp_f32_e32 v152, v152
	v_add_f32_e32 v192, v151, v192
	v_exp_f32_e32 v153, v153
	v_add_f32_e32 v192, v152, v192
	s_waitcnt lgkmcnt(12)
	v_mfma_f32_32x32x16_bf16 v[156:171], v[234:237], v[84:87], v[156:171]
	v_exp_f32_e32 v154, v154
	v_add_f32_e32 v192, v153, v192
	v_exp_f32_e32 v155, v155
	v_add_f32_e32 v192, v154, v192
	v_cvt_pk_bf16_f32 v144, v148, v149
	v_add_f32_e32 v192, v155, v192
	v_cvt_pk_bf16_f32 v145, v150, v151
	v_cvt_pk_bf16_f32 v146, v152, v153
	v_cvt_pk_bf16_f32 v147, v154, v155
	v_add_f32_e32 v0, v0, v192
	s_waitcnt lgkmcnt(8)
	ds_read_b64_tr_b16 v[172:173], v247 offset:9216
	ds_read_b64_tr_b16 v[174:175], v247 offset:10752
	ds_read_b64_tr_b16 v[176:177], v247 offset:9280
	ds_read_b64_tr_b16 v[178:179], v247 offset:10816
	v_mfma_f32_32x32x16_bf16 v[32:47], v[188:191], v[140:143], v[32:47]
	v_exp_f32_e32 v156, v156
	v_exp_f32_e32 v157, v157
	v_exp_f32_e32 v158, v158
	v_add_f32_e32 v192, v156, v157
	v_exp_f32_e32 v159, v159
	v_add_f32_e32 v192, v158, v192
	v_exp_f32_e32 v160, v160
	v_add_f32_e32 v192, v159, v192
	v_exp_f32_e32 v161, v161
	v_add_f32_e32 v192, v160, v192
	v_mfma_f32_32x32x16_bf16 v[16:31], v[206:209], v[140:143], v[16:31]
	v_exp_f32_e32 v162, v162
	v_add_f32_e32 v192, v161, v192
	v_exp_f32_e32 v163, v163
	v_add_f32_e32 v192, v162, v192
	v_cvt_pk_bf16_f32 v156, v156, v157
	v_add_f32_e32 v192, v163, v192
	v_cvt_pk_bf16_f32 v157, v158, v159
	v_cvt_pk_bf16_f32 v158, v160, v161
	v_cvt_pk_bf16_f32 v159, v162, v163
	v_exp_f32_e32 v164, v164
	s_waitcnt lgkmcnt(10)
	v_mfma_f32_32x32x16_bf16 v[32:47], v[238:241], v[144:147], v[32:47]
	v_exp_f32_e32 v165, v165
	v_add_f32_e32 v192, v164, v192
	v_exp_f32_e32 v166, v166
	v_add_f32_e32 v192, v165, v192
	v_exp_f32_e32 v167, v167
	v_add_f32_e32 v192, v166, v192
	v_exp_f32_e32 v168, v168
	v_add_f32_e32 v192, v167, v192
	v_exp_f32_e32 v169, v169
	v_add_f32_e32 v192, v168, v192
	s_waitcnt lgkmcnt(8)
	v_mfma_f32_32x32x16_bf16 v[16:31], v[242:245], v[144:147], v[16:31]
	v_exp_f32_e32 v170, v170
	v_add_f32_e32 v192, v169, v192
	v_exp_f32_e32 v171, v171
	v_add_f32_e32 v192, v170, v192
	v_cvt_pk_bf16_f32 v160, v164, v165
	v_add_f32_e32 v192, v171, v192
	v_cvt_pk_bf16_f32 v161, v166, v167
	v_cvt_pk_bf16_f32 v162, v168, v169
	v_cvt_pk_bf16_f32 v163, v170, v171
	v_add_f32_e32 v0, v0, v192
	s_nop 1
	s_waitcnt lgkmcnt(6)
	v_mfma_f32_32x32x16_bf16 v[32:47], v[180:183], v[156:159], v[32:47]
	s_waitcnt lgkmcnt(4)
	v_mfma_f32_32x32x16_bf16 v[16:31], v[184:187], v[156:159], v[16:31]
	s_waitcnt lgkmcnt(2)
	v_mfma_f32_32x32x16_bf16 v[32:47], v[172:175], v[160:163], v[32:47]
	s_waitcnt lgkmcnt(0)
	v_mfma_f32_32x32x16_bf16 v[16:31], v[176:179], v[160:163], v[16:31]
	s_branch .LBB0_234
